# k12 + the same wave-half re-pairing around the two GEMM2 epilogues
# speedup vs baseline: 1.0210x; 1.0042x over previous
.LBB0_816:
	s_add_u32 s26, s36, s38
	ds_read_b128 v[134:137], v164
	ds_read_b128 v[138:141], v164 offset:1024
	ds_read_b128 v[142:145], v164 offset:2048
	ds_read_b128 v[170:173], v164 offset:3072
	s_addc_u32 s27, s37, s39
	s_add_u32 s26, s26, 0xcd48100
	s_addc_u32 s27, s27, 0
	s_add_u32 s56, s74, s38
	s_addc_u32 s57, s75, s39
	s_cmpk_eq_i32 s38, 0x300
	s_cselect_b32 s59, s15, s27
	s_cselect_b32 s58, s1, s26
	s_cselect_b32 s57, s33, s57
	s_cselect_b32 s56, s25, s56
	s_mov_b32 m0, s60
	v_lshl_add_u64 v[146:147], v[128:129], 0, s[38:39]
	ds_read_b128 v[174:177], v165
	ds_read_b128 v[178:181], v165 offset:1024
	ds_read_b128 v[182:185], v165 offset:2048
	ds_read_b128 v[186:189], v165 offset:3072
	ds_read_b128 v[190:193], v165 offset:4096
	ds_read_b128 v[194:197], v165 offset:5120
	ds_read_b128 v[198:201], v165 offset:6144
	ds_read_b128 v[210:213], v165 offset:7168
	global_load_lds_dwordx4 v[146:147], off
	v_lshl_add_u64 v[146:147], v[130:131], 0, s[38:39]
	s_mov_b32 m0, s61
	s_nop 0
	global_load_lds_dwordx4 v[146:147], off
	s_waitcnt lgkmcnt(8)
	s_barrier
	s_waitcnt lgkmcnt(0)
	s_setprio 1
	s_waitcnt lgkmcnt(0)
	v_mfma_f32_16x16x32_bf16 v[124:127], v[134:137], v[174:177], v[124:127]
	v_mfma_f32_16x16x32_bf16 v[120:123], v[142:145], v[174:177], v[120:123]
	v_mfma_f32_16x16x32_bf16 v[116:119], v[134:137], v[182:185], v[116:119]
	v_mfma_f32_16x16x32_bf16 v[112:115], v[142:145], v[182:185], v[112:115]
	v_mfma_f32_16x16x32_bf16 v[100:103], v[134:137], v[190:193], v[100:103]
	v_mfma_f32_16x16x32_bf16 v[92:95], v[142:145], v[190:193], v[92:95]
	v_mfma_f32_16x16x32_bf16 v[84:87], v[134:137], v[198:201], v[84:87]
	v_mfma_f32_16x16x32_bf16 v[76:79], v[142:145], v[198:201], v[76:79]
	v_mfma_f32_16x16x32_bf16 v[124:127], v[138:141], v[178:181], v[124:127]
	v_mfma_f32_16x16x32_bf16 v[120:123], v[170:173], v[178:181], v[120:123]
	v_mfma_f32_16x16x32_bf16 v[116:119], v[138:141], v[186:189], v[116:119]
	v_mfma_f32_16x16x32_bf16 v[112:115], v[170:173], v[186:189], v[112:115]
	v_mfma_f32_16x16x32_bf16 v[100:103], v[138:141], v[194:197], v[100:103]
	v_mfma_f32_16x16x32_bf16 v[92:95], v[170:173], v[194:197], v[92:95]
	v_mfma_f32_16x16x32_bf16 v[84:87], v[138:141], v[210:213], v[84:87]
	v_mfma_f32_16x16x32_bf16 v[76:79], v[170:173], v[210:213], v[76:79]
	s_setprio 0
	s_barrier
	s_mov_b32 m0, s62
	v_lshl_add_u64 v[146:147], s[56:57], 0, v[150:151]
	ds_read_b128 v[214:217], v166
	ds_read_b128 v[218:221], v166 offset:1024
	ds_read_b128 v[222:225], v166 offset:2048
	ds_read_b128 v[226:229], v166 offset:3072
	global_load_lds_dwordx4 v[146:147], off
	v_lshl_add_u64 v[160:161], s[56:57], 0, v[154:155]
	s_mov_b32 m0, s63
	s_nop 0
	global_load_lds_dwordx4 v[160:161], off
	s_barrier
	s_waitcnt lgkmcnt(0)
	s_setprio 1
	s_waitcnt lgkmcnt(0)
	v_mfma_f32_16x16x32_bf16 v[108:111], v[214:217], v[174:177], v[108:111]
	v_mfma_f32_16x16x32_bf16 v[104:107], v[222:225], v[174:177], v[104:107]
	v_mfma_f32_16x16x32_bf16 v[96:99], v[214:217], v[182:185], v[96:99]
	v_mfma_f32_16x16x32_bf16 v[88:91], v[222:225], v[182:185], v[88:91]
	v_mfma_f32_16x16x32_bf16 v[80:83], v[214:217], v[190:193], v[80:83]
	v_mfma_f32_16x16x32_bf16 v[72:75], v[222:225], v[190:193], v[72:75]
	v_mfma_f32_16x16x32_bf16 v[68:71], v[214:217], v[198:201], v[68:71]
	v_mfma_f32_16x16x32_bf16 v[64:67], v[222:225], v[198:201], v[64:67]
	v_mfma_f32_16x16x32_bf16 v[108:111], v[218:221], v[178:181], v[108:111]
	v_mfma_f32_16x16x32_bf16 v[104:107], v[226:229], v[178:181], v[104:107]
	v_mfma_f32_16x16x32_bf16 v[96:99], v[218:221], v[186:189], v[96:99]
	v_mfma_f32_16x16x32_bf16 v[88:91], v[226:229], v[186:189], v[88:91]
	v_mfma_f32_16x16x32_bf16 v[80:83], v[218:221], v[194:197], v[80:83]
	v_mfma_f32_16x16x32_bf16 v[72:75], v[226:229], v[194:197], v[72:75]
	v_mfma_f32_16x16x32_bf16 v[68:71], v[218:221], v[210:213], v[68:71]
	v_mfma_f32_16x16x32_bf16 v[64:67], v[226:229], v[210:213], v[64:67]
	s_setprio 0
	s_mov_b32 m0, s19
	v_lshl_add_u64 v[230:231], s[58:59], 0, v[148:149]
	s_barrier
	ds_read_b128 v[174:177], v165 offset:16384
	ds_read_b128 v[178:181], v165 offset:17408
	ds_read_b128 v[182:185], v165 offset:18432
	ds_read_b128 v[186:189], v165 offset:19456
	ds_read_b128 v[190:193], v165 offset:20480
	ds_read_b128 v[194:197], v165 offset:21504
	ds_read_b128 v[198:201], v165 offset:22528
	ds_read_b128 v[210:213], v165 offset:23552
	global_load_lds_dwordx4 v[230:231], off
	v_lshl_add_u64 v[232:233], s[58:59], 0, v[152:153]
	s_mov_b32 m0, s20
	s_nop 0
	global_load_lds_dwordx4 v[232:233], off
	s_barrier
	s_waitcnt lgkmcnt(0)
	s_setprio 1
	s_waitcnt lgkmcnt(0)
	v_mfma_f32_16x16x32_bf16 v[60:63], v[134:137], v[174:177], v[60:63]
	v_mfma_f32_16x16x32_bf16 v[56:59], v[142:145], v[174:177], v[56:59]
	v_mfma_f32_16x16x32_bf16 v[48:51], v[134:137], v[182:185], v[48:51]
	v_mfma_f32_16x16x32_bf16 v[40:43], v[142:145], v[182:185], v[40:43]
	v_mfma_f32_16x16x32_bf16 v[32:35], v[134:137], v[190:193], v[32:35]
	v_mfma_f32_16x16x32_bf16 v[24:27], v[142:145], v[190:193], v[24:27]
	v_mfma_f32_16x16x32_bf16 v[16:19], v[134:137], v[198:201], v[16:19]
	v_mfma_f32_16x16x32_bf16 v[8:11], v[142:145], v[198:201], v[8:11]
	v_mfma_f32_16x16x32_bf16 v[60:63], v[138:141], v[178:181], v[60:63]
	v_mfma_f32_16x16x32_bf16 v[56:59], v[170:173], v[178:181], v[56:59]
	v_mfma_f32_16x16x32_bf16 v[48:51], v[138:141], v[186:189], v[48:51]
	v_mfma_f32_16x16x32_bf16 v[40:43], v[170:173], v[186:189], v[40:43]
	v_mfma_f32_16x16x32_bf16 v[32:35], v[138:141], v[194:197], v[32:35]
	v_mfma_f32_16x16x32_bf16 v[24:27], v[170:173], v[194:197], v[24:27]
	v_mfma_f32_16x16x32_bf16 v[16:19], v[138:141], v[210:213], v[16:19]
	v_mfma_f32_16x16x32_bf16 v[8:11], v[170:173], v[210:213], v[8:11]
	s_setprio 0
	s_barrier
	s_add_u32 s82, s56, 0x40000
	s_addc_u32 s83, s57, 0
	s_mov_b32 m0, s64
	v_lshl_add_u64 v[134:135], s[82:83], 0, v[150:151]
	global_load_lds_dwordx4 v[134:135], off
	v_lshl_add_u64 v[134:135], s[82:83], 0, v[154:155]
	s_mov_b32 m0, s65
	s_nop 0
	global_load_lds_dwordx4 v[134:135], off
	s_waitcnt vmcnt(6)
	s_barrier
	s_setprio 1
	v_mfma_f32_16x16x32_bf16 v[52:55], v[214:217], v[174:177], v[52:55]
	v_mfma_f32_16x16x32_bf16 v[44:47], v[222:225], v[174:177], v[44:47]
	v_mfma_f32_16x16x32_bf16 v[36:39], v[214:217], v[182:185], v[36:39]
	v_mfma_f32_16x16x32_bf16 v[28:31], v[222:225], v[182:185], v[28:31]
	v_mfma_f32_16x16x32_bf16 v[20:23], v[214:217], v[190:193], v[20:23]
	v_mfma_f32_16x16x32_bf16 v[12:15], v[222:225], v[190:193], v[12:15]
	v_mfma_f32_16x16x32_bf16 v[4:7], v[214:217], v[198:201], v[4:7]
	v_mfma_f32_16x16x32_bf16 v[0:3], v[222:225], v[198:201], v[0:3]
	v_mfma_f32_16x16x32_bf16 v[52:55], v[218:221], v[178:181], v[52:55]
	v_mfma_f32_16x16x32_bf16 v[44:47], v[226:229], v[178:181], v[44:47]
	v_mfma_f32_16x16x32_bf16 v[36:39], v[218:221], v[186:189], v[36:39]
	v_mfma_f32_16x16x32_bf16 v[28:31], v[226:229], v[186:189], v[28:31]
	v_mfma_f32_16x16x32_bf16 v[20:23], v[218:221], v[194:197], v[20:23]
	v_mfma_f32_16x16x32_bf16 v[12:15], v[226:229], v[194:197], v[12:15]
	v_mfma_f32_16x16x32_bf16 v[4:7], v[218:221], v[210:213], v[4:7]
	v_mfma_f32_16x16x32_bf16 v[0:3], v[226:229], v[210:213], v[0:3]
	s_setprio 0
	s_barrier
	ds_read_b128 v[134:137], v167
	ds_read_b128 v[138:141], v167 offset:1024
	ds_read_b128 v[142:145], v167 offset:2048
	ds_read_b128 v[170:173], v167 offset:3072
	s_add_u32 s58, s58, 0x40000
	s_addc_u32 s59, s59, 0
	s_mov_b32 m0, s21
	v_lshl_add_u64 v[214:215], s[58:59], 0, v[148:149]
	ds_read_b128 v[174:177], v165 offset:32768
	ds_read_b128 v[178:181], v165 offset:33792
	ds_read_b128 v[182:185], v165 offset:34816
	ds_read_b128 v[186:189], v165 offset:35840
	ds_read_b128 v[190:193], v165 offset:36864
	ds_read_b128 v[194:197], v165 offset:37888
	ds_read_b128 v[198:201], v165 offset:38912
	ds_read_b128 v[210:213], v165 offset:39936
	global_load_lds_dwordx4 v[214:215], off
	v_lshl_add_u64 v[214:215], s[58:59], 0, v[152:153]
	s_mov_b32 m0, s22
	s_nop 0
	global_load_lds_dwordx4 v[214:215], off
	s_waitcnt lgkmcnt(8)
	s_barrier
	s_waitcnt lgkmcnt(0)
	s_setprio 1
	s_waitcnt lgkmcnt(0)
	v_mfma_f32_16x16x32_bf16 v[124:127], v[134:137], v[174:177], v[124:127]
	v_mfma_f32_16x16x32_bf16 v[120:123], v[142:145], v[174:177], v[120:123]
	v_mfma_f32_16x16x32_bf16 v[116:119], v[134:137], v[182:185], v[116:119]
	v_mfma_f32_16x16x32_bf16 v[112:115], v[142:145], v[182:185], v[112:115]
	v_mfma_f32_16x16x32_bf16 v[100:103], v[134:137], v[190:193], v[100:103]
	v_mfma_f32_16x16x32_bf16 v[92:95], v[142:145], v[190:193], v[92:95]
	v_mfma_f32_16x16x32_bf16 v[84:87], v[134:137], v[198:201], v[84:87]
	v_mfma_f32_16x16x32_bf16 v[76:79], v[142:145], v[198:201], v[76:79]
	v_mfma_f32_16x16x32_bf16 v[124:127], v[138:141], v[178:181], v[124:127]
	v_mfma_f32_16x16x32_bf16 v[120:123], v[170:173], v[178:181], v[120:123]
	v_mfma_f32_16x16x32_bf16 v[116:119], v[138:141], v[186:189], v[116:119]
	v_mfma_f32_16x16x32_bf16 v[112:115], v[170:173], v[186:189], v[112:115]
	v_mfma_f32_16x16x32_bf16 v[100:103], v[138:141], v[194:197], v[100:103]
	v_mfma_f32_16x16x32_bf16 v[92:95], v[170:173], v[194:197], v[92:95]
	v_mfma_f32_16x16x32_bf16 v[84:87], v[138:141], v[210:213], v[84:87]
	v_mfma_f32_16x16x32_bf16 v[76:79], v[170:173], v[210:213], v[76:79]
	s_setprio 0
	s_barrier
	s_mov_b32 m0, s66
	v_lshl_add_u64 v[146:147], v[146:147], 0, s[16:17]
	ds_read_b128 v[214:217], v168
	ds_read_b128 v[218:221], v168 offset:1024
	ds_read_b128 v[222:225], v168 offset:2048
	ds_read_b128 v[226:229], v168 offset:3072
	global_load_lds_dwordx4 v[146:147], off
	v_lshl_add_u64 v[146:147], v[160:161], 0, s[16:17]
	s_mov_b32 m0, s67
	s_nop 0
	global_load_lds_dwordx4 v[146:147], off
	s_barrier
	s_waitcnt lgkmcnt(0)
	s_setprio 1
	s_waitcnt lgkmcnt(0)
	v_mfma_f32_16x16x32_bf16 v[108:111], v[214:217], v[174:177], v[108:111]
	v_mfma_f32_16x16x32_bf16 v[104:107], v[222:225], v[174:177], v[104:107]
	v_mfma_f32_16x16x32_bf16 v[96:99], v[214:217], v[182:185], v[96:99]
	v_mfma_f32_16x16x32_bf16 v[88:91], v[222:225], v[182:185], v[88:91]
	v_mfma_f32_16x16x32_bf16 v[80:83], v[214:217], v[190:193], v[80:83]
	v_mfma_f32_16x16x32_bf16 v[72:75], v[222:225], v[190:193], v[72:75]
	v_mfma_f32_16x16x32_bf16 v[68:71], v[214:217], v[198:201], v[68:71]
	v_mfma_f32_16x16x32_bf16 v[64:67], v[222:225], v[198:201], v[64:67]
	v_mfma_f32_16x16x32_bf16 v[108:111], v[218:221], v[178:181], v[108:111]
	v_mfma_f32_16x16x32_bf16 v[104:107], v[226:229], v[178:181], v[104:107]
	v_mfma_f32_16x16x32_bf16 v[96:99], v[218:221], v[186:189], v[96:99]
	v_mfma_f32_16x16x32_bf16 v[88:91], v[226:229], v[186:189], v[88:91]
	v_mfma_f32_16x16x32_bf16 v[80:83], v[218:221], v[194:197], v[80:83]
	v_mfma_f32_16x16x32_bf16 v[72:75], v[226:229], v[194:197], v[72:75]
	v_mfma_f32_16x16x32_bf16 v[68:71], v[218:221], v[210:213], v[68:71]
	v_mfma_f32_16x16x32_bf16 v[64:67], v[226:229], v[210:213], v[64:67]
	s_setprio 0
	s_mov_b32 m0, s23
	v_lshl_add_u64 v[146:147], v[230:231], 0, s[16:17]
	s_barrier
	ds_read_b128 v[174:177], v165 offset:49152
	ds_read_b128 v[178:181], v165 offset:50176
	ds_read_b128 v[182:185], v165 offset:51200
	ds_read_b128 v[186:189], v165 offset:52224
	ds_read_b128 v[190:193], v165 offset:53248
	ds_read_b128 v[194:197], v165 offset:54272
	ds_read_b128 v[198:201], v165 offset:55296
	ds_read_b128 v[210:213], v165 offset:56320
	global_load_lds_dwordx4 v[146:147], off
	v_lshl_add_u64 v[146:147], v[232:233], 0, s[16:17]
	s_mov_b32 m0, s24
	s_nop 0
	global_load_lds_dwordx4 v[146:147], off
	s_barrier
	s_waitcnt lgkmcnt(0)
	s_setprio 1
	s_waitcnt lgkmcnt(0)
	v_mfma_f32_16x16x32_bf16 v[60:63], v[134:137], v[174:177], v[60:63]
	v_mfma_f32_16x16x32_bf16 v[56:59], v[142:145], v[174:177], v[56:59]
	v_mfma_f32_16x16x32_bf16 v[48:51], v[134:137], v[182:185], v[48:51]
	v_mfma_f32_16x16x32_bf16 v[40:43], v[142:145], v[182:185], v[40:43]
	v_mfma_f32_16x16x32_bf16 v[32:35], v[134:137], v[190:193], v[32:35]
	v_mfma_f32_16x16x32_bf16 v[24:27], v[142:145], v[190:193], v[24:27]
	v_mfma_f32_16x16x32_bf16 v[16:19], v[134:137], v[198:201], v[16:19]
	v_mfma_f32_16x16x32_bf16 v[8:11], v[142:145], v[198:201], v[8:11]
	v_mfma_f32_16x16x32_bf16 v[60:63], v[138:141], v[178:181], v[60:63]
	v_mfma_f32_16x16x32_bf16 v[56:59], v[170:173], v[178:181], v[56:59]
	v_mfma_f32_16x16x32_bf16 v[48:51], v[138:141], v[186:189], v[48:51]
	v_mfma_f32_16x16x32_bf16 v[40:43], v[170:173], v[186:189], v[40:43]
	v_mfma_f32_16x16x32_bf16 v[32:35], v[138:141], v[194:197], v[32:35]
	v_mfma_f32_16x16x32_bf16 v[24:27], v[170:173], v[194:197], v[24:27]
	v_mfma_f32_16x16x32_bf16 v[16:19], v[138:141], v[210:213], v[16:19]
	v_mfma_f32_16x16x32_bf16 v[8:11], v[170:173], v[210:213], v[8:11]
	s_setprio 0
	s_barrier
	s_add_u32 s56, s56, 0x40080
	s_addc_u32 s57, s57, 0
	s_mov_b32 m0, s68
	v_lshl_add_u64 v[134:135], s[56:57], 0, v[150:151]
	global_load_lds_dwordx4 v[134:135], off
	v_lshl_add_u64 v[134:135], s[56:57], 0, v[154:155]
	s_mov_b32 m0, s69
	s_nop 0
	global_load_lds_dwordx4 v[134:135], off
	s_waitcnt vmcnt(6)
	s_barrier
	s_setprio 1
	v_mfma_f32_16x16x32_bf16 v[52:55], v[214:217], v[174:177], v[52:55]
	v_mfma_f32_16x16x32_bf16 v[44:47], v[222:225], v[174:177], v[44:47]
	v_mfma_f32_16x16x32_bf16 v[36:39], v[214:217], v[182:185], v[36:39]
	v_mfma_f32_16x16x32_bf16 v[28:31], v[222:225], v[182:185], v[28:31]
	v_mfma_f32_16x16x32_bf16 v[20:23], v[214:217], v[190:193], v[20:23]
	v_mfma_f32_16x16x32_bf16 v[12:15], v[222:225], v[190:193], v[12:15]
	v_mfma_f32_16x16x32_bf16 v[4:7], v[214:217], v[198:201], v[4:7]
	v_mfma_f32_16x16x32_bf16 v[0:3], v[222:225], v[198:201], v[0:3]
	v_mfma_f32_16x16x32_bf16 v[52:55], v[218:221], v[178:181], v[52:55]
	v_mfma_f32_16x16x32_bf16 v[44:47], v[226:229], v[178:181], v[44:47]
	v_mfma_f32_16x16x32_bf16 v[36:39], v[218:221], v[186:189], v[36:39]
	v_mfma_f32_16x16x32_bf16 v[28:31], v[226:229], v[186:189], v[28:31]
	v_mfma_f32_16x16x32_bf16 v[20:23], v[218:221], v[194:197], v[20:23]
	v_mfma_f32_16x16x32_bf16 v[12:15], v[226:229], v[194:197], v[12:15]
	v_mfma_f32_16x16x32_bf16 v[4:7], v[218:221], v[210:213], v[4:7]
	v_mfma_f32_16x16x32_bf16 v[0:3], v[226:229], v[210:213], v[0:3]
	s_setprio 0
	s_add_i32 s80, s80, 2
	s_add_u32 s38, s38, 0x100
	s_addc_u32 s39, s39, 0
	s_cmp_gt_u32 s80, 5
	s_barrier
	s_cbranch_scc0 .LBB0_816
	s_cmpk_gt_u32 s13, 0xff
	s_cbranch_scc1 .Lus3
	s_barrier
.Lus3:
	s_sext_i32_i8 s4, s4
	s_mul_i32 s8, s8, 0x240000
	s_lshl_b32 s4, s4, 17
	v_or3_b32 v128, s18, v132, v163
	s_add_i32 s4, s8, s4
	v_lshlrev_b32_e32 v169, 1, v128
	s_add_i32 s4, s4, 0xa0000
	v_add_u32_e32 v132, s4, v169
	v_mov_b32_e32 v133, 0
	s_mov_b32 s4, 0x10000
	v_lshl_add_u64 v[160:161], s[70:71], 0, v[132:133]
	global_load_dwordx4 v[128:131], v132, s[70:71]
	v_add_co_u32_e32 v132, vcc, s4, v160
	s_mov_b32 s4, 0x123000
	s_nop 0
	v_addc_co_u32_e32 v133, vcc, 0, v161, vcc
	v_add_co_u32_e32 v136, vcc, 0x1000, v160
	global_load_dwordx4 v[132:135], v[132:133], off
	s_nop 0
	v_addc_co_u32_e32 v137, vcc, 0, v161, vcc
	global_load_dwordx4 v[144:147], v[136:137], off
	v_add_co_u32_e32 v136, vcc, 0x11000, v160
	s_mov_b32 s8, 0x120000
	s_nop 0
	v_addc_co_u32_e32 v137, vcc, 0, v161, vcc
	global_load_dwordx4 v[140:143], v[136:137], off
	v_add_co_u32_e32 v136, vcc, 0x2000, v160
	s_add_u32 s2, s78, s2
	s_nop 0
	v_addc_co_u32_e32 v137, vcc, 0, v161, vcc
	global_load_dwordx4 v[170:173], v[136:137], off
	v_add_co_u32_e32 v136, vcc, s4, v160
	s_mov_b32 s4, 0x131000
	s_nop 0
	v_addc_co_u32_e32 v137, vcc, 0, v161, vcc
	v_add_co_u32_e32 v174, vcc, s8, v160
	s_addc_u32 s3, s79, s3
	s_nop 0
	v_addc_co_u32_e32 v175, vcc, 0, v161, vcc
	v_add_co_u32_e32 v178, vcc, 0x12000, v160
	global_load_dwordx4 v[136:139], v[136:137], off
	s_nop 0
	global_load_dwordx4 v[174:177], v[174:175], off
	v_addc_co_u32_e32 v179, vcc, 0, v161, vcc
	v_add_co_u32_e32 v182, vcc, 0x3000, v160
	global_load_dwordx4 v[178:181], v[178:179], off
	s_nop 0
	v_addc_co_u32_e32 v183, vcc, 0, v161, vcc
	v_add_co_u32_e32 v186, vcc, 0x13000, v160
	s_add_u32 s38, s2, 0x36c8500
	s_nop 0
	v_addc_co_u32_e32 v187, vcc, 0, v161, vcc
	global_load_dwordx4 v[182:185], v[182:183], off
	s_nop 0
	global_load_dwordx4 v[186:189], v[186:187], off
	s_addc_u32 s39, s3, 0
	s_sub_i32 s2, s5, s73
	s_lshl_b32 s3, s72, 5
	s_sub_i32 s2, s2, s3
	s_sext_i32_i8 s2, s2
	s_add_i32 s2, s9, s2
	s_ashr_i32 s3, s2, 31
	s_lshl_b64 s[2:3], s[2:3], 19
	s_add_u32 s2, s78, s2
	s_addc_u32 s3, s79, s3
	s_mov_b32 s56, -2
	s_mov_b64 s[8:9], 0x80
	s_waitcnt vmcnt(0)
	v_lshlrev_b32_e32 v190, 16, v128
	v_and_b32_e32 v191, 0xffff0000, v128
	v_lshlrev_b32_e32 v128, 16, v129
	v_and_b32_e32 v129, 0xffff0000, v129
	v_lshlrev_b32_e32 v192, 16, v130
	v_and_b32_e32 v193, 0xffff0000, v130
	v_lshlrev_b32_e32 v130, 16, v131
	v_and_b32_e32 v131, 0xffff0000, v131
	v_pk_mul_f32 v[126:127], v[126:127], v[128:129]
	v_pk_mul_f32 v[122:123], v[122:123], v[130:131]
	v_lshlrev_b32_e32 v128, 16, v132
	v_and_b32_e32 v129, 0xffff0000, v132
	v_lshlrev_b32_e32 v130, 16, v133
	v_and_b32_e32 v131, 0xffff0000, v133
	v_lshlrev_b32_e32 v132, 16, v134
	v_and_b32_e32 v133, 0xffff0000, v134
	v_pk_mul_f32 v[132:133], v[104:105], v[132:133]
	v_lshlrev_b32_e32 v104, 16, v144
	v_and_b32_e32 v105, 0xffff0000, v144
	v_pk_mul_f32 v[124:125], v[124:125], v[190:191]
	v_lshlrev_b32_e32 v134, 16, v135
	v_and_b32_e32 v135, 0xffff0000, v135
	v_pk_mul_f32 v[116:117], v[116:117], v[104:105]
	v_lshlrev_b32_e32 v104, 16, v146
	v_and_b32_e32 v105, 0xffff0000, v146
	v_add_co_u32_e32 v190, vcc, s4, v160
	v_pk_mul_f32 v[134:135], v[106:107], v[134:135]
	v_lshlrev_b32_e32 v106, 16, v145
	v_and_b32_e32 v107, 0xffff0000, v145
	v_pk_mul_f32 v[112:113], v[112:113], v[104:105]
	v_lshlrev_b32_e32 v104, 16, v140
	v_and_b32_e32 v105, 0xffff0000, v140
	v_addc_co_u32_e32 v191, vcc, 0, v161, vcc
	s_mov_b32 s4, 0x122000
	v_pk_mul_f32 v[120:121], v[120:121], v[192:193]
	v_pk_mul_f32 v[118:119], v[118:119], v[106:107]
	v_lshlrev_b32_e32 v106, 16, v147
	v_and_b32_e32 v107, 0xffff0000, v147
	v_pk_mul_f32 v[104:105], v[96:97], v[104:105]
	v_lshlrev_b32_e32 v96, 16, v142
	v_and_b32_e32 v97, 0xffff0000, v142
	global_load_dwordx4 v[144:147], v[190:191], off offset:-4096
	v_add_co_u32_e32 v192, vcc, s4, v160
	v_pk_mul_f32 v[128:129], v[108:109], v[128:129]
	v_pk_mul_f32 v[114:115], v[114:115], v[106:107]
	v_lshlrev_b32_e32 v106, 16, v141
	v_and_b32_e32 v107, 0xffff0000, v141
	v_pk_mul_f32 v[108:109], v[88:89], v[96:97]
	v_lshlrev_b32_e32 v88, 16, v170
	v_and_b32_e32 v89, 0xffff0000, v170
	v_addc_co_u32_e32 v193, vcc, 0, v161, vcc
	v_pk_mul_f32 v[106:107], v[98:99], v[106:107]
	v_lshlrev_b32_e32 v98, 16, v143
	v_and_b32_e32 v99, 0xffff0000, v143
	global_load_dwordx4 v[140:143], v[192:193], off offset:-4096
	v_pk_mul_f32 v[96:97], v[100:101], v[88:89]
	v_lshlrev_b32_e32 v88, 16, v172
	v_and_b32_e32 v89, 0xffff0000, v172
	v_pk_mul_f32 v[130:131], v[110:111], v[130:131]
	v_pk_mul_f32 v[110:111], v[90:91], v[98:99]
	v_lshlrev_b32_e32 v90, 16, v171
	v_and_b32_e32 v91, 0xffff0000, v171
	v_pk_mul_f32 v[100:101], v[92:93], v[88:89]
	v_lshlrev_b32_e32 v88, 16, v178
	v_and_b32_e32 v89, 0xffff0000, v178
	v_pk_mul_f32 v[98:99], v[102:103], v[90:91]
	v_lshlrev_b32_e32 v90, 16, v173
	v_and_b32_e32 v91, 0xffff0000, v173
	global_load_dwordx4 v[170:173], v[190:191], off
	v_pk_mul_f32 v[88:89], v[80:81], v[88:89]
	v_lshlrev_b32_e32 v80, 16, v180
	v_and_b32_e32 v81, 0xffff0000, v180
	v_pk_mul_f32 v[102:103], v[94:95], v[90:91]
	v_lshlrev_b32_e32 v90, 16, v179
	v_and_b32_e32 v91, 0xffff0000, v179
	v_pk_mul_f32 v[92:93], v[72:73], v[80:81]
	v_lshlrev_b32_e32 v72, 16, v182
	v_and_b32_e32 v73, 0xffff0000, v182
	s_mov_b32 s4, 0x133000
	v_pk_mul_f32 v[90:91], v[82:83], v[90:91]
	v_lshlrev_b32_e32 v82, 16, v181
	v_and_b32_e32 v83, 0xffff0000, v181
	global_load_dwordx4 v[178:181], v[192:193], off
	v_pk_mul_f32 v[80:81], v[84:85], v[72:73]
	v_add_co_u32_e32 v84, vcc, s4, v160
	v_pk_mul_f32 v[94:95], v[74:75], v[82:83]
	s_nop 0
	v_addc_co_u32_e32 v85, vcc, 0, v161, vcc
	global_load_dwordx4 v[190:193], v[84:85], off offset:-4096
	v_lshlrev_b32_e32 v74, 16, v183
	v_and_b32_e32 v75, 0xffff0000, v183
	v_pk_mul_f32 v[82:83], v[86:87], v[74:75]
	global_load_dwordx4 v[84:87], v[84:85], off
	v_lshlrev_b32_e32 v72, 16, v184
	v_and_b32_e32 v73, 0xffff0000, v184
	v_lshlrev_b32_e32 v74, 16, v185
	v_and_b32_e32 v75, 0xffff0000, v185
	v_pk_mul_f32 v[78:79], v[78:79], v[74:75]
	v_pk_mul_f32 v[76:77], v[76:77], v[72:73]
	v_lshlrev_b32_e32 v72, 16, v186
	v_and_b32_e32 v73, 0xffff0000, v186
	v_lshlrev_b32_e32 v74, 16, v187
	v_and_b32_e32 v75, 0xffff0000, v187
	v_pk_mul_f32 v[70:71], v[70:71], v[74:75]
	v_pk_mul_f32 v[68:69], v[68:69], v[72:73]
	v_lshlrev_b32_e32 v72, 16, v188
	v_and_b32_e32 v73, 0xffff0000, v188
	v_lshlrev_b32_e32 v74, 16, v189
	v_and_b32_e32 v75, 0xffff0000, v189
	v_pk_mul_f32 v[74:75], v[66:67], v[74:75]
	v_pk_mul_f32 v[72:73], v[64:65], v[72:73]
	v_lshlrev_b32_e32 v64, 16, v174
	v_and_b32_e32 v65, 0xffff0000, v174
	v_lshlrev_b32_e32 v66, 16, v175
	v_and_b32_e32 v67, 0xffff0000, v175
	v_pk_mul_f32 v[62:63], v[62:63], v[66:67]
	v_pk_mul_f32 v[60:61], v[60:61], v[64:65]
	v_lshlrev_b32_e32 v64, 16, v176
	v_and_b32_e32 v65, 0xffff0000, v176
	v_lshlrev_b32_e32 v66, 16, v177
	v_and_b32_e32 v67, 0xffff0000, v177
	v_pk_mul_f32 v[66:67], v[58:59], v[66:67]
	v_pk_mul_f32 v[64:65], v[56:57], v[64:65]
	s_waitcnt vmcnt(0)
	v_lshlrev_b32_e32 v56, 16, v144
	v_and_b32_e32 v57, 0xffff0000, v144
	v_lshlrev_b32_e32 v58, 16, v145
	v_and_b32_e32 v59, 0xffff0000, v145
	v_pk_mul_f32 v[54:55], v[54:55], v[58:59]
	v_pk_mul_f32 v[52:53], v[52:53], v[56:57]
	v_lshlrev_b32_e32 v56, 16, v146
	v_and_b32_e32 v57, 0xffff0000, v146
	v_lshlrev_b32_e32 v58, 16, v147
	v_and_b32_e32 v59, 0xffff0000, v147
	v_pk_mul_f32 v[58:59], v[46:47], v[58:59]
	v_pk_mul_f32 v[56:57], v[44:45], v[56:57]
	v_lshlrev_b32_e32 v44, 16, v140
	v_and_b32_e32 v45, 0xffff0000, v140
	v_lshlrev_b32_e32 v46, 16, v141
	v_and_b32_e32 v47, 0xffff0000, v141
	v_pk_mul_f32 v[46:47], v[50:51], v[46:47]
	v_pk_mul_f32 v[44:45], v[48:49], v[44:45]
	v_lshlrev_b32_e32 v48, 16, v142
	v_and_b32_e32 v49, 0xffff0000, v142
	v_lshlrev_b32_e32 v50, 16, v143
	v_and_b32_e32 v51, 0xffff0000, v143
	v_pk_mul_f32 v[50:51], v[42:43], v[50:51]
	v_pk_mul_f32 v[48:49], v[40:41], v[48:49]
	v_lshlrev_b32_e32 v40, 16, v170
	v_and_b32_e32 v41, 0xffff0000, v170
	v_lshlrev_b32_e32 v42, 16, v171
	v_and_b32_e32 v43, 0xffff0000, v171
	v_pk_mul_f32 v[38:39], v[38:39], v[42:43]
	v_pk_mul_f32 v[36:37], v[36:37], v[40:41]
	v_lshlrev_b32_e32 v40, 16, v172
	v_and_b32_e32 v41, 0xffff0000, v172
	v_lshlrev_b32_e32 v42, 16, v173
	v_and_b32_e32 v43, 0xffff0000, v173
	v_pk_mul_f32 v[42:43], v[30:31], v[42:43]
	v_pk_mul_f32 v[40:41], v[28:29], v[40:41]
	s_mov_b64 s[4:5], 0xcd88480
	v_lshlrev_b32_e32 v28, 16, v178
	v_and_b32_e32 v29, 0xffff0000, v178
	v_lshlrev_b32_e32 v30, 16, v179
	v_and_b32_e32 v31, 0xffff0000, v179
	v_pk_mul_f32 v[30:31], v[34:35], v[30:31]
	v_pk_mul_f32 v[28:29], v[32:33], v[28:29]
	v_lshlrev_b32_e32 v32, 16, v180
	v_and_b32_e32 v33, 0xffff0000, v180
	v_lshlrev_b32_e32 v34, 16, v181
	v_and_b32_e32 v35, 0xffff0000, v181
	v_pk_mul_f32 v[34:35], v[26:27], v[34:35]
	v_pk_mul_f32 v[32:33], v[24:25], v[32:33]
	v_lshlrev_b32_e32 v24, 16, v190
	v_and_b32_e32 v25, 0xffff0000, v190
	v_lshlrev_b32_e32 v26, 16, v191
	v_and_b32_e32 v27, 0xffff0000, v191
	v_pk_mul_f32 v[22:23], v[22:23], v[26:27]
	v_pk_mul_f32 v[20:21], v[20:21], v[24:25]
	v_lshlrev_b32_e32 v24, 16, v192
	v_and_b32_e32 v25, 0xffff0000, v192
	v_lshlrev_b32_e32 v26, 16, v193
	v_and_b32_e32 v27, 0xffff0000, v193
	v_pk_mul_f32 v[26:27], v[14:15], v[26:27]
	v_pk_mul_f32 v[24:25], v[12:13], v[24:25]
	v_lshlrev_b32_e32 v12, 16, v136
	v_and_b32_e32 v13, 0xffff0000, v136
	v_lshlrev_b32_e32 v14, 16, v137
	v_and_b32_e32 v15, 0xffff0000, v137
	v_pk_mul_f32 v[14:15], v[18:19], v[14:15]
	v_pk_mul_f32 v[12:13], v[16:17], v[12:13]
	v_lshlrev_b32_e32 v16, 16, v138
	v_and_b32_e32 v17, 0xffff0000, v138
	v_lshlrev_b32_e32 v18, 16, v139
	v_and_b32_e32 v19, 0xffff0000, v139
	v_pk_mul_f32 v[10:11], v[10:11], v[18:19]
	v_pk_mul_f32 v[8:9], v[8:9], v[16:17]
	v_lshlrev_b32_e32 v16, 16, v84
	v_and_b32_e32 v17, 0xffff0000, v84
	v_lshlrev_b32_e32 v18, 16, v85
	v_and_b32_e32 v19, 0xffff0000, v85
	v_pk_mul_f32 v[6:7], v[6:7], v[18:19]
	v_pk_mul_f32 v[4:5], v[4:5], v[16:17]
	v_lshlrev_b32_e32 v16, 16, v86
	v_and_b32_e32 v17, 0xffff0000, v86
	v_lshlrev_b32_e32 v18, 16, v87
	v_and_b32_e32 v19, 0xffff0000, v87
	v_pk_mul_f32 v[2:3], v[2:3], v[18:19]
	v_pk_mul_f32 v[0:1], v[0:1], v[16:17]
	v_lshl_add_u64 v[16:17], s[2:3], 0, v[156:157]
	v_lshl_add_u64 v[18:19], s[2:3], 0, v[158:159]
	v_lshl_add_u64 v[16:17], v[16:17], 0, s[4:5]
	v_lshl_add_u64 v[18:19], v[18:19], 0, s[4:5]
	s_mov_b64 s[4:5], 0
	s_cmpk_gt_u32 s13, 0xff
	s_cbranch_scc0 .Lus4
	s_barrier
.Lus4:
.LBB0_818:
	s_add_u32 s16, s2, s4
	ds_read_b128 v[84:87], v164
	ds_read_b128 v[136:139], v164 offset:1024
	ds_read_b128 v[140:143], v164 offset:2048
	ds_read_b128 v[144:147], v164 offset:3072
	s_addc_u32 s17, s3, s5
	s_add_u32 s16, s16, 0xcd48500
	s_addc_u32 s17, s17, 0
	s_add_u32 s26, s38, s4
	s_addc_u32 s27, s39, s5
	s_cmpk_eq_i32 s4, 0x300
	s_cselect_b32 s37, s15, s17
	s_cselect_b32 s36, s1, s16
	s_cselect_b32 s17, s33, s27
	s_cselect_b32 s16, s25, s26
	s_mov_b32 m0, s60
	v_lshl_add_u64 v[160:161], v[16:17], 0, s[4:5]
	ds_read_b128 v[156:159], v165
	ds_read_b128 v[170:173], v165 offset:1024
	ds_read_b128 v[174:177], v165 offset:2048
	ds_read_b128 v[178:181], v165 offset:3072
	ds_read_b128 v[182:185], v165 offset:4096
	ds_read_b128 v[186:189], v165 offset:5120
	ds_read_b128 v[190:193], v165 offset:6144
	ds_read_b128 v[194:197], v165 offset:7168
	global_load_lds_dwordx4 v[160:161], off
	v_lshl_add_u64 v[160:161], v[18:19], 0, s[4:5]
	s_mov_b32 m0, s61
	s_nop 0
	global_load_lds_dwordx4 v[160:161], off
	s_waitcnt lgkmcnt(8)
	s_barrier
	s_waitcnt lgkmcnt(0)
	s_setprio 1
	s_waitcnt lgkmcnt(0)
	v_mfma_f32_16x16x32_bf16 v[124:127], v[84:87], v[156:159], v[124:127]
	v_mfma_f32_16x16x32_bf16 v[120:123], v[140:143], v[156:159], v[120:123]
	v_mfma_f32_16x16x32_bf16 v[116:119], v[84:87], v[174:177], v[116:119]
	v_mfma_f32_16x16x32_bf16 v[112:115], v[140:143], v[174:177], v[112:115]
	v_mfma_f32_16x16x32_bf16 v[96:99], v[84:87], v[182:185], v[96:99]
	v_mfma_f32_16x16x32_bf16 v[100:103], v[140:143], v[182:185], v[100:103]
	v_mfma_f32_16x16x32_bf16 v[80:83], v[84:87], v[190:193], v[80:83]
	v_mfma_f32_16x16x32_bf16 v[76:79], v[140:143], v[190:193], v[76:79]
	v_mfma_f32_16x16x32_bf16 v[124:127], v[136:139], v[170:173], v[124:127]
	v_mfma_f32_16x16x32_bf16 v[120:123], v[144:147], v[170:173], v[120:123]
	v_mfma_f32_16x16x32_bf16 v[116:119], v[136:139], v[178:181], v[116:119]
	v_mfma_f32_16x16x32_bf16 v[112:115], v[144:147], v[178:181], v[112:115]
	v_mfma_f32_16x16x32_bf16 v[96:99], v[136:139], v[186:189], v[96:99]
	v_mfma_f32_16x16x32_bf16 v[100:103], v[144:147], v[186:189], v[100:103]
	v_mfma_f32_16x16x32_bf16 v[80:83], v[136:139], v[194:197], v[80:83]
	v_mfma_f32_16x16x32_bf16 v[76:79], v[144:147], v[194:197], v[76:79]
	s_setprio 0
	s_barrier
	s_mov_b32 m0, s62
	v_lshl_add_u64 v[160:161], s[16:17], 0, v[150:151]
	ds_read_b128 v[198:201], v166
	ds_read_b128 v[210:213], v166 offset:1024
	ds_read_b128 v[214:217], v166 offset:2048
	ds_read_b128 v[218:221], v166 offset:3072
	global_load_lds_dwordx4 v[160:161], off
	v_lshl_add_u64 v[222:223], s[16:17], 0, v[154:155]
	s_mov_b32 m0, s63
	s_nop 0
	global_load_lds_dwordx4 v[222:223], off
	s_barrier
	s_waitcnt lgkmcnt(0)
	s_setprio 1
	s_waitcnt lgkmcnt(0)
	v_mfma_f32_16x16x32_bf16 v[128:131], v[198:201], v[156:159], v[128:131]
	v_mfma_f32_16x16x32_bf16 v[132:135], v[214:217], v[156:159], v[132:135]
	v_mfma_f32_16x16x32_bf16 v[104:107], v[198:201], v[174:177], v[104:107]
	v_mfma_f32_16x16x32_bf16 v[108:111], v[214:217], v[174:177], v[108:111]
	v_mfma_f32_16x16x32_bf16 v[88:91], v[198:201], v[182:185], v[88:91]
	v_mfma_f32_16x16x32_bf16 v[92:95], v[214:217], v[182:185], v[92:95]
	v_mfma_f32_16x16x32_bf16 v[68:71], v[198:201], v[190:193], v[68:71]
	v_mfma_f32_16x16x32_bf16 v[72:75], v[214:217], v[190:193], v[72:75]
	v_mfma_f32_16x16x32_bf16 v[128:131], v[210:213], v[170:173], v[128:131]
	v_mfma_f32_16x16x32_bf16 v[132:135], v[218:221], v[170:173], v[132:135]
	v_mfma_f32_16x16x32_bf16 v[104:107], v[210:213], v[178:181], v[104:107]
	v_mfma_f32_16x16x32_bf16 v[108:111], v[218:221], v[178:181], v[108:111]
	v_mfma_f32_16x16x32_bf16 v[88:91], v[210:213], v[186:189], v[88:91]
	v_mfma_f32_16x16x32_bf16 v[92:95], v[218:221], v[186:189], v[92:95]
	v_mfma_f32_16x16x32_bf16 v[68:71], v[210:213], v[194:197], v[68:71]
	v_mfma_f32_16x16x32_bf16 v[72:75], v[218:221], v[194:197], v[72:75]
	s_setprio 0
	s_mov_b32 m0, s19
	v_lshl_add_u64 v[224:225], s[36:37], 0, v[148:149]
	s_barrier
	ds_read_b128 v[156:159], v165 offset:16384
	ds_read_b128 v[170:173], v165 offset:17408
	ds_read_b128 v[174:177], v165 offset:18432
	ds_read_b128 v[178:181], v165 offset:19456
	ds_read_b128 v[182:185], v165 offset:20480
	ds_read_b128 v[186:189], v165 offset:21504
	ds_read_b128 v[190:193], v165 offset:22528
	ds_read_b128 v[194:197], v165 offset:23552
	global_load_lds_dwordx4 v[224:225], off
	v_lshl_add_u64 v[226:227], s[36:37], 0, v[152:153]
	s_mov_b32 m0, s20
	s_nop 0
	global_load_lds_dwordx4 v[226:227], off
	s_barrier
	s_waitcnt lgkmcnt(0)
	s_setprio 1
	s_waitcnt lgkmcnt(0)
	v_mfma_f32_16x16x32_bf16 v[60:63], v[84:87], v[156:159], v[60:63]
	v_mfma_f32_16x16x32_bf16 v[64:67], v[140:143], v[156:159], v[64:67]
	v_mfma_f32_16x16x32_bf16 v[44:47], v[84:87], v[174:177], v[44:47]
	v_mfma_f32_16x16x32_bf16 v[48:51], v[140:143], v[174:177], v[48:51]
	v_mfma_f32_16x16x32_bf16 v[28:31], v[84:87], v[182:185], v[28:31]
	v_mfma_f32_16x16x32_bf16 v[32:35], v[140:143], v[182:185], v[32:35]
	v_mfma_f32_16x16x32_bf16 v[12:15], v[84:87], v[190:193], v[12:15]
	v_mfma_f32_16x16x32_bf16 v[8:11], v[140:143], v[190:193], v[8:11]
	v_mfma_f32_16x16x32_bf16 v[60:63], v[136:139], v[170:173], v[60:63]
	v_mfma_f32_16x16x32_bf16 v[64:67], v[144:147], v[170:173], v[64:67]
	v_mfma_f32_16x16x32_bf16 v[44:47], v[136:139], v[178:181], v[44:47]
	v_mfma_f32_16x16x32_bf16 v[48:51], v[144:147], v[178:181], v[48:51]
	v_mfma_f32_16x16x32_bf16 v[28:31], v[136:139], v[186:189], v[28:31]
	v_mfma_f32_16x16x32_bf16 v[32:35], v[144:147], v[186:189], v[32:35]
	v_mfma_f32_16x16x32_bf16 v[12:15], v[136:139], v[194:197], v[12:15]
	v_mfma_f32_16x16x32_bf16 v[8:11], v[144:147], v[194:197], v[8:11]
	s_setprio 0
	s_barrier
	s_add_u32 s58, s16, 0x40000
	s_addc_u32 s59, s17, 0
	s_mov_b32 m0, s64
	v_lshl_add_u64 v[84:85], s[58:59], 0, v[150:151]
	global_load_lds_dwordx4 v[84:85], off
	v_lshl_add_u64 v[84:85], s[58:59], 0, v[154:155]
	s_mov_b32 m0, s65
	s_nop 0
	global_load_lds_dwordx4 v[84:85], off
	s_waitcnt vmcnt(6)
	s_barrier
	s_setprio 1
	v_mfma_f32_16x16x32_bf16 v[52:55], v[198:201], v[156:159], v[52:55]
	v_mfma_f32_16x16x32_bf16 v[56:59], v[214:217], v[156:159], v[56:59]
	v_mfma_f32_16x16x32_bf16 v[36:39], v[198:201], v[174:177], v[36:39]
	v_mfma_f32_16x16x32_bf16 v[40:43], v[214:217], v[174:177], v[40:43]
	v_mfma_f32_16x16x32_bf16 v[20:23], v[198:201], v[182:185], v[20:23]
	v_mfma_f32_16x16x32_bf16 v[24:27], v[214:217], v[182:185], v[24:27]
	v_mfma_f32_16x16x32_bf16 v[4:7], v[198:201], v[190:193], v[4:7]
	v_mfma_f32_16x16x32_bf16 v[0:3], v[214:217], v[190:193], v[0:3]
	v_mfma_f32_16x16x32_bf16 v[52:55], v[210:213], v[170:173], v[52:55]
	v_mfma_f32_16x16x32_bf16 v[56:59], v[218:221], v[170:173], v[56:59]
	v_mfma_f32_16x16x32_bf16 v[36:39], v[210:213], v[178:181], v[36:39]
	v_mfma_f32_16x16x32_bf16 v[40:43], v[218:221], v[178:181], v[40:43]
	v_mfma_f32_16x16x32_bf16 v[20:23], v[210:213], v[186:189], v[20:23]
	v_mfma_f32_16x16x32_bf16 v[24:27], v[218:221], v[186:189], v[24:27]
	v_mfma_f32_16x16x32_bf16 v[4:7], v[210:213], v[194:197], v[4:7]
	v_mfma_f32_16x16x32_bf16 v[0:3], v[218:221], v[194:197], v[0:3]
	s_setprio 0
	s_barrier
	ds_read_b128 v[84:87], v167
	ds_read_b128 v[136:139], v167 offset:1024
	ds_read_b128 v[140:143], v167 offset:2048
	ds_read_b128 v[144:147], v167 offset:3072
	s_add_u32 s36, s36, 0x40000
	s_addc_u32 s37, s37, 0
	s_mov_b32 m0, s21
	v_lshl_add_u64 v[198:199], s[36:37], 0, v[148:149]
	ds_read_b128 v[156:159], v165 offset:32768
	ds_read_b128 v[170:173], v165 offset:33792
	ds_read_b128 v[174:177], v165 offset:34816
	ds_read_b128 v[178:181], v165 offset:35840
	ds_read_b128 v[182:185], v165 offset:36864
	ds_read_b128 v[186:189], v165 offset:37888
	ds_read_b128 v[190:193], v165 offset:38912
	ds_read_b128 v[194:197], v165 offset:39936
	global_load_lds_dwordx4 v[198:199], off
	v_lshl_add_u64 v[198:199], s[36:37], 0, v[152:153]
	s_mov_b32 m0, s22
	s_nop 0
	global_load_lds_dwordx4 v[198:199], off
	s_waitcnt lgkmcnt(8)
	s_barrier
	s_waitcnt lgkmcnt(0)
	s_setprio 1
	s_waitcnt lgkmcnt(0)
	v_mfma_f32_16x16x32_bf16 v[124:127], v[84:87], v[156:159], v[124:127]
	v_mfma_f32_16x16x32_bf16 v[120:123], v[140:143], v[156:159], v[120:123]
	v_mfma_f32_16x16x32_bf16 v[116:119], v[84:87], v[174:177], v[116:119]
	v_mfma_f32_16x16x32_bf16 v[112:115], v[140:143], v[174:177], v[112:115]
	v_mfma_f32_16x16x32_bf16 v[96:99], v[84:87], v[182:185], v[96:99]
	v_mfma_f32_16x16x32_bf16 v[100:103], v[140:143], v[182:185], v[100:103]
	v_mfma_f32_16x16x32_bf16 v[80:83], v[84:87], v[190:193], v[80:83]
	v_mfma_f32_16x16x32_bf16 v[76:79], v[140:143], v[190:193], v[76:79]
	v_mfma_f32_16x16x32_bf16 v[124:127], v[136:139], v[170:173], v[124:127]
	v_mfma_f32_16x16x32_bf16 v[120:123], v[144:147], v[170:173], v[120:123]
	v_mfma_f32_16x16x32_bf16 v[116:119], v[136:139], v[178:181], v[116:119]
	v_mfma_f32_16x16x32_bf16 v[112:115], v[144:147], v[178:181], v[112:115]
	v_mfma_f32_16x16x32_bf16 v[96:99], v[136:139], v[186:189], v[96:99]
	v_mfma_f32_16x16x32_bf16 v[100:103], v[144:147], v[186:189], v[100:103]
	v_mfma_f32_16x16x32_bf16 v[80:83], v[136:139], v[194:197], v[80:83]
	v_mfma_f32_16x16x32_bf16 v[76:79], v[144:147], v[194:197], v[76:79]
	s_setprio 0
	s_barrier
	s_mov_b32 m0, s66
	v_lshl_add_u64 v[160:161], v[160:161], 0, s[8:9]
	ds_read_b128 v[198:201], v168
	ds_read_b128 v[210:213], v168 offset:1024
	ds_read_b128 v[214:217], v168 offset:2048
	ds_read_b128 v[218:221], v168 offset:3072
	global_load_lds_dwordx4 v[160:161], off
	v_lshl_add_u64 v[160:161], v[222:223], 0, s[8:9]
	s_mov_b32 m0, s67
	s_nop 0
	global_load_lds_dwordx4 v[160:161], off
	s_barrier
	s_waitcnt lgkmcnt(0)
	s_setprio 1
	s_waitcnt lgkmcnt(0)
	v_mfma_f32_16x16x32_bf16 v[128:131], v[198:201], v[156:159], v[128:131]
	v_mfma_f32_16x16x32_bf16 v[132:135], v[214:217], v[156:159], v[132:135]
	v_mfma_f32_16x16x32_bf16 v[104:107], v[198:201], v[174:177], v[104:107]
	v_mfma_f32_16x16x32_bf16 v[108:111], v[214:217], v[174:177], v[108:111]
	v_mfma_f32_16x16x32_bf16 v[88:91], v[198:201], v[182:185], v[88:91]
	v_mfma_f32_16x16x32_bf16 v[92:95], v[214:217], v[182:185], v[92:95]
	v_mfma_f32_16x16x32_bf16 v[68:71], v[198:201], v[190:193], v[68:71]
	v_mfma_f32_16x16x32_bf16 v[72:75], v[214:217], v[190:193], v[72:75]
	v_mfma_f32_16x16x32_bf16 v[128:131], v[210:213], v[170:173], v[128:131]
	v_mfma_f32_16x16x32_bf16 v[132:135], v[218:221], v[170:173], v[132:135]
	v_mfma_f32_16x16x32_bf16 v[104:107], v[210:213], v[178:181], v[104:107]
	v_mfma_f32_16x16x32_bf16 v[108:111], v[218:221], v[178:181], v[108:111]
	v_mfma_f32_16x16x32_bf16 v[88:91], v[210:213], v[186:189], v[88:91]
	v_mfma_f32_16x16x32_bf16 v[92:95], v[218:221], v[186:189], v[92:95]
	v_mfma_f32_16x16x32_bf16 v[68:71], v[210:213], v[194:197], v[68:71]
	v_mfma_f32_16x16x32_bf16 v[72:75], v[218:221], v[194:197], v[72:75]
	s_setprio 0
	s_mov_b32 m0, s23
	v_lshl_add_u64 v[160:161], v[224:225], 0, s[8:9]
	s_barrier
	ds_read_b128 v[156:159], v165 offset:49152
	ds_read_b128 v[170:173], v165 offset:50176
	ds_read_b128 v[174:177], v165 offset:51200
	ds_read_b128 v[178:181], v165 offset:52224
	ds_read_b128 v[182:185], v165 offset:53248
	ds_read_b128 v[186:189], v165 offset:54272
	ds_read_b128 v[190:193], v165 offset:55296
	ds_read_b128 v[194:197], v165 offset:56320
	global_load_lds_dwordx4 v[160:161], off
	v_lshl_add_u64 v[160:161], v[226:227], 0, s[8:9]
	s_mov_b32 m0, s24
	s_nop 0
	global_load_lds_dwordx4 v[160:161], off
	s_barrier
	s_waitcnt lgkmcnt(0)
	s_setprio 1
	s_waitcnt lgkmcnt(0)
	v_mfma_f32_16x16x32_bf16 v[60:63], v[84:87], v[156:159], v[60:63]
	v_mfma_f32_16x16x32_bf16 v[64:67], v[140:143], v[156:159], v[64:67]
	v_mfma_f32_16x16x32_bf16 v[44:47], v[84:87], v[174:177], v[44:47]
	v_mfma_f32_16x16x32_bf16 v[48:51], v[140:143], v[174:177], v[48:51]
	v_mfma_f32_16x16x32_bf16 v[28:31], v[84:87], v[182:185], v[28:31]
	v_mfma_f32_16x16x32_bf16 v[32:35], v[140:143], v[182:185], v[32:35]
	v_mfma_f32_16x16x32_bf16 v[12:15], v[84:87], v[190:193], v[12:15]
	v_mfma_f32_16x16x32_bf16 v[8:11], v[140:143], v[190:193], v[8:11]
	v_mfma_f32_16x16x32_bf16 v[60:63], v[136:139], v[170:173], v[60:63]
	v_mfma_f32_16x16x32_bf16 v[64:67], v[144:147], v[170:173], v[64:67]
	v_mfma_f32_16x16x32_bf16 v[44:47], v[136:139], v[178:181], v[44:47]
	v_mfma_f32_16x16x32_bf16 v[48:51], v[144:147], v[178:181], v[48:51]
	v_mfma_f32_16x16x32_bf16 v[28:31], v[136:139], v[186:189], v[28:31]
	v_mfma_f32_16x16x32_bf16 v[32:35], v[144:147], v[186:189], v[32:35]
	v_mfma_f32_16x16x32_bf16 v[12:15], v[136:139], v[194:197], v[12:15]
	v_mfma_f32_16x16x32_bf16 v[8:11], v[144:147], v[194:197], v[8:11]
	s_setprio 0
	s_barrier
	s_add_u32 s16, s16, 0x40080
	s_addc_u32 s17, s17, 0
	s_mov_b32 m0, s68
	v_lshl_add_u64 v[84:85], s[16:17], 0, v[150:151]
	global_load_lds_dwordx4 v[84:85], off
	v_lshl_add_u64 v[84:85], s[16:17], 0, v[154:155]
	s_mov_b32 m0, s69
	s_nop 0
	global_load_lds_dwordx4 v[84:85], off
	s_waitcnt vmcnt(6)
	s_barrier
	s_setprio 1
	v_mfma_f32_16x16x32_bf16 v[52:55], v[198:201], v[156:159], v[52:55]
	v_mfma_f32_16x16x32_bf16 v[56:59], v[214:217], v[156:159], v[56:59]
	v_mfma_f32_16x16x32_bf16 v[36:39], v[198:201], v[174:177], v[36:39]
	v_mfma_f32_16x16x32_bf16 v[40:43], v[214:217], v[174:177], v[40:43]
	v_mfma_f32_16x16x32_bf16 v[20:23], v[198:201], v[182:185], v[20:23]
	v_mfma_f32_16x16x32_bf16 v[24:27], v[214:217], v[182:185], v[24:27]
	v_mfma_f32_16x16x32_bf16 v[4:7], v[198:201], v[190:193], v[4:7]
	v_mfma_f32_16x16x32_bf16 v[0:3], v[214:217], v[190:193], v[0:3]
	v_mfma_f32_16x16x32_bf16 v[52:55], v[210:213], v[170:173], v[52:55]
	v_mfma_f32_16x16x32_bf16 v[56:59], v[218:221], v[170:173], v[56:59]
	v_mfma_f32_16x16x32_bf16 v[36:39], v[210:213], v[178:181], v[36:39]
	v_mfma_f32_16x16x32_bf16 v[40:43], v[218:221], v[178:181], v[40:43]
	v_mfma_f32_16x16x32_bf16 v[20:23], v[210:213], v[186:189], v[20:23]
	v_mfma_f32_16x16x32_bf16 v[24:27], v[218:221], v[186:189], v[24:27]
	v_mfma_f32_16x16x32_bf16 v[4:7], v[210:213], v[194:197], v[4:7]
	v_mfma_f32_16x16x32_bf16 v[0:3], v[218:221], v[194:197], v[0:3]
	s_setprio 0
	s_add_i32 s56, s56, 2
	s_add_u32 s4, s4, 0x100
	s_addc_u32 s5, s5, 0
	s_cmp_lt_u32 s56, 6
	s_barrier
	s_cbranch_scc1 .LBB0_818
	s_cmpk_gt_u32 s13, 0xff
	s_cbranch_scc1 .Lus5
	s_barrier
.Lus5:
	s_sext_i32_i8 s2, s0
	s_mul_i32 s0, s14, 0x240000
	s_lshl_b32 s1, s2, 17
	s_add_i32 s0, s0, s1
	s_add_i32 s0, s0, 0xa8000
	v_add_u32_e32 v16, s0, v169
	v_mov_b32_e32 v17, 0
	v_lshl_add_u64 v[86:87], s[70:71], 0, v[16:17]
	v_add_co_u32_e32 v18, vcc, 0x10000, v86
	v_lshl_add_u32 v136, s14, 8, v162
	s_nop 0
	v_addc_co_u32_e32 v19, vcc, 0, v87, vcc
	global_load_dwordx4 v[140:143], v[18:19], off
	v_add_co_u32_e32 v18, vcc, 0x1000, v86
	v_lshl_or_b32 v85, s2, 8, v163
	s_nop 0
	v_addc_co_u32_e32 v19, vcc, 0, v87, vcc
	global_load_dwordx4 v[144:147], v[18:19], off
	global_load_dwordx4 v[148:151], v16, s[70:71]
	v_add_co_u32_e32 v16, vcc, 0x11000, v86
	v_ashrrev_i32_e32 v137, 31, v136
	s_nop 0
	v_addc_co_u32_e32 v17, vcc, 0, v87, vcc
	v_add_co_u32_e32 v156, vcc, 0x2000, v86
	global_load_dwordx4 v[152:155], v[16:17], off
	s_mov_b64 s[0:1], vcc
	v_add_co_u32_e32 v160, vcc, 0x12000, v86
	s_mov_b64 s[8:9], vcc
	v_add_co_u32_e32 v164, vcc, 0x3000, v86
	v_or_b32_e32 v138, s18, v85
	s_mov_b64 s[4:5], vcc
	v_add_co_u32_e32 v16, vcc, 0x13000, v86
	v_or_b32_e32 v84, 16, v136
	v_lshlrev_b64 v[158:159], 11, v[136:137]
	v_ashrrev_i32_e32 v139, 31, v138
	v_addc_co_u32_e32 v17, vcc, 0, v87, vcc
	v_ashrrev_i32_e32 v85, 31, v84
	v_lshl_add_u64 v[158:159], s[10:11], 0, v[158:159]
	v_lshlrev_b64 v[138:139], 1, v[138:139]
	v_addc_co_u32_e64 v157, vcc, 0, v87, s[0:1]
	global_load_dwordx4 v[16:19], v[16:17], off
	v_lshlrev_b64 v[168:169], 11, v[84:85]
	v_lshl_add_u64 v[84:85], v[158:159], 0, v[138:139]
	global_load_dwordx4 v[156:159], v[156:157], off
	v_addc_co_u32_e64 v161, vcc, 0, v87, s[8:9]
	v_addc_co_u32_e64 v165, vcc, 0, v87, s[4:5]
	global_load_dwordx4 v[160:163], v[160:161], off
	s_nop 0
	global_load_dwordx4 v[164:167], v[164:165], off
	s_mov_b32 s0, 0x120000
	v_readlane_b32 s80, v234, 43
	s_cmpk_gt_u32 s13, 0xff
	v_readlane_b32 s81, v234, 44
	s_waitcnt vmcnt(0)
	v_lshlrev_b32_e32 v172, 16, v140
	v_and_b32_e32 v173, 0xffff0000, v140
	v_lshlrev_b32_e32 v140, 16, v141
	v_and_b32_e32 v141, 0xffff0000, v141
	v_lshlrev_b32_e32 v170, 16, v142
	v_and_b32_e32 v171, 0xffff0000, v142
	v_lshlrev_b32_e32 v142, 16, v143
	v_and_b32_e32 v143, 0xffff0000, v143
	v_pk_mul_f32 v[130:131], v[130:131], v[140:141]
	v_pk_mul_f32 v[128:129], v[128:129], v[172:173]
	v_pk_mul_f32 v[134:135], v[134:135], v[142:143]
	v_pk_mul_f32 v[132:133], v[132:133], v[170:171]
	v_cvt_pk_bf16_f32 v128, v128, v129
	v_cvt_pk_bf16_f32 v129, v130, v131
	v_cvt_pk_bf16_f32 v131, v134, v135
	v_lshlrev_b32_e32 v134, 16, v149
	v_cvt_pk_bf16_f32 v130, v132, v133
	global_store_dwordx4 v[84:85], v[128:131], off offset:256
	v_lshlrev_b32_e32 v132, 16, v148
	v_and_b32_e32 v133, 0xffff0000, v148
	v_lshlrev_b32_e32 v128, 16, v150
	v_and_b32_e32 v129, 0xffff0000, v150
	v_lshlrev_b32_e32 v130, 16, v151
	v_and_b32_e32 v131, 0xffff0000, v151
	v_and_b32_e32 v135, 0xffff0000, v149
	v_pk_mul_f32 v[130:131], v[122:123], v[130:131]
	v_pk_mul_f32 v[122:123], v[120:121], v[128:129]
	v_pk_mul_f32 v[120:121], v[124:125], v[132:133]
	v_pk_mul_f32 v[126:127], v[126:127], v[134:135]
	v_cvt_pk_bf16_f32 v120, v120, v121
	v_lshlrev_b32_e32 v140, 16, v146
	v_cvt_pk_bf16_f32 v121, v126, v127
	v_cvt_pk_bf16_f32 v122, v122, v123
	v_cvt_pk_bf16_f32 v123, v130, v131
	global_store_dwordx4 v[84:85], v[120:123], off
	v_and_b32_e32 v141, 0xffff0000, v146
	s_nop 0
	v_lshlrev_b32_e32 v120, 16, v147
	v_and_b32_e32 v121, 0xffff0000, v147
	v_pk_mul_f32 v[120:121], v[114:115], v[120:121]
	v_pk_mul_f32 v[114:115], v[112:113], v[140:141]
	v_lshlrev_b32_e32 v112, 16, v144
	v_and_b32_e32 v113, 0xffff0000, v144
	v_lshlrev_b32_e32 v122, 16, v145
	v_and_b32_e32 v123, 0xffff0000, v145
	v_pk_mul_f32 v[112:113], v[116:117], v[112:113]
	v_lshl_add_u64 v[116:117], s[10:11], 0, v[168:169]
	v_pk_mul_f32 v[118:119], v[118:119], v[122:123]
	v_cvt_pk_bf16_f32 v112, v112, v113
	v_cvt_pk_bf16_f32 v114, v114, v115
	v_cvt_pk_bf16_f32 v115, v120, v121
	v_lshl_add_u64 v[116:117], v[116:117], 0, v[138:139]
	v_cvt_pk_bf16_f32 v113, v118, v119
	global_store_dwordx4 v[116:117], v[112:115], off
	s_nop 1
	v_lshlrev_b32_e32 v112, 16, v154
	v_and_b32_e32 v113, 0xffff0000, v154
	v_lshlrev_b32_e32 v114, 16, v155
	v_and_b32_e32 v115, 0xffff0000, v155
	v_pk_mul_f32 v[110:111], v[110:111], v[114:115]
	v_pk_mul_f32 v[108:109], v[108:109], v[112:113]
	v_lshlrev_b32_e32 v112, 16, v152
	v_and_b32_e32 v113, 0xffff0000, v152
	v_lshlrev_b32_e32 v114, 16, v153
	v_and_b32_e32 v115, 0xffff0000, v153
	v_pk_mul_f32 v[106:107], v[106:107], v[114:115]
	v_pk_mul_f32 v[104:105], v[104:105], v[112:113]
	s_nop 0
	v_cvt_pk_bf16_f32 v104, v104, v105
	v_cvt_pk_bf16_f32 v105, v106, v107
	v_cvt_pk_bf16_f32 v106, v108, v109
	v_cvt_pk_bf16_f32 v107, v110, v111
	global_store_dwordx4 v[116:117], v[104:107], off offset:256
	v_lshlrev_b32_e32 v108, 16, v159
	v_and_b32_e32 v109, 0xffff0000, v159
	v_or_b32_e32 v104, 32, v136
	v_lshlrev_b32_e32 v106, 16, v158
	v_and_b32_e32 v107, 0xffff0000, v158
	v_ashrrev_i32_e32 v105, 31, v104
	v_pk_mul_f32 v[102:103], v[102:103], v[108:109]
	v_pk_mul_f32 v[100:101], v[100:101], v[106:107]
	v_lshlrev_b32_e32 v106, 16, v156
	v_and_b32_e32 v107, 0xffff0000, v156
	v_lshlrev_b32_e32 v108, 16, v157
	v_and_b32_e32 v109, 0xffff0000, v157
	v_lshlrev_b64 v[104:105], 11, v[104:105]
	v_pk_mul_f32 v[98:99], v[98:99], v[108:109]
	v_pk_mul_f32 v[96:97], v[96:97], v[106:107]
	s_nop 0
	v_cvt_pk_bf16_f32 v96, v96, v97
	v_cvt_pk_bf16_f32 v97, v98, v99
	v_cvt_pk_bf16_f32 v98, v100, v101
	v_lshl_add_u64 v[100:101], s[10:11], 0, v[104:105]
	v_lshl_add_u64 v[100:101], v[100:101], 0, v[138:139]
	v_cvt_pk_bf16_f32 v99, v102, v103
	global_store_dwordx4 v[100:101], v[96:99], off
	s_nop 1
	v_lshlrev_b32_e32 v96, 16, v162
	v_and_b32_e32 v97, 0xffff0000, v162
	v_lshlrev_b32_e32 v98, 16, v163
	v_and_b32_e32 v99, 0xffff0000, v163
	v_pk_mul_f32 v[92:93], v[92:93], v[96:97]
	v_lshlrev_b32_e32 v96, 16, v160
	v_and_b32_e32 v97, 0xffff0000, v160
	v_pk_mul_f32 v[94:95], v[94:95], v[98:99]
	v_lshlrev_b32_e32 v98, 16, v161
	v_and_b32_e32 v99, 0xffff0000, v161
	v_pk_mul_f32 v[88:89], v[88:89], v[96:97]
	v_pk_mul_f32 v[90:91], v[90:91], v[98:99]
	v_cvt_pk_bf16_f32 v88, v88, v89
	s_nop 0
	v_cvt_pk_bf16_f32 v89, v90, v91
	v_cvt_pk_bf16_f32 v90, v92, v93
	v_cvt_pk_bf16_f32 v91, v94, v95
	global_store_dwordx4 v[100:101], v[88:91], off offset:256
	v_lshlrev_b32_e32 v92, 16, v167
	v_and_b32_e32 v93, 0xffff0000, v167
	v_or_b32_e32 v88, 48, v136
	v_ashrrev_i32_e32 v89, 31, v88
	v_lshlrev_b32_e32 v90, 16, v166
	v_and_b32_e32 v91, 0xffff0000, v166
	v_lshlrev_b64 v[88:89], 11, v[88:89]
	v_pk_mul_f32 v[92:93], v[78:79], v[92:93]
	v_pk_mul_f32 v[78:79], v[76:77], v[90:91]
	v_lshlrev_b32_e32 v76, 16, v164
	v_and_b32_e32 v77, 0xffff0000, v164
	v_lshlrev_b32_e32 v90, 16, v165
	v_and_b32_e32 v91, 0xffff0000, v165
	v_pk_mul_f32 v[76:77], v[80:81], v[76:77]
	v_lshl_add_u64 v[80:81], s[10:11], 0, v[88:89]
	v_pk_mul_f32 v[82:83], v[82:83], v[90:91]
	v_cvt_pk_bf16_f32 v76, v76, v77
	v_lshl_add_u64 v[80:81], v[80:81], 0, v[138:139]
	v_cvt_pk_bf16_f32 v77, v82, v83
	v_cvt_pk_bf16_f32 v78, v78, v79
	v_cvt_pk_bf16_f32 v79, v92, v93
	global_store_dwordx4 v[80:81], v[76:79], off
	s_nop 1
	v_lshlrev_b32_e32 v76, 16, v18
	v_and_b32_e32 v77, 0xffff0000, v18
	v_lshlrev_b32_e32 v18, 16, v19
	v_and_b32_e32 v19, 0xffff0000, v19
	v_pk_mul_f32 v[74:75], v[74:75], v[18:19]
	v_pk_mul_f32 v[18:19], v[72:73], v[76:77]
	v_lshlrev_b32_e32 v72, 16, v16
	v_and_b32_e32 v73, 0xffff0000, v16
	v_lshlrev_b32_e32 v16, 16, v17
	v_and_b32_e32 v17, 0xffff0000, v17
	v_pk_mul_f32 v[70:71], v[70:71], v[16:17]
	v_pk_mul_f32 v[16:17], v[68:69], v[72:73]
	v_cvt_pk_bf16_f32 v18, v18, v19
	v_cvt_pk_bf16_f32 v19, v74, v75
	s_nop 0
	v_cvt_pk_bf16_f32 v16, v16, v17
	v_cvt_pk_bf16_f32 v17, v70, v71
	global_store_dwordx4 v[80:81], v[16:19], off offset:256
	s_nop 1
	v_add_co_u32_e32 v16, vcc, s0, v86
	s_mov_b32 s0, 0x131000
	s_nop 0
	v_addc_co_u32_e32 v17, vcc, 0, v87, vcc
	global_load_dwordx4 v[72:75], v[16:17], off
	v_add_co_u32_e32 v16, vcc, s0, v86
	s_mov_b32 s0, 0x122000
	s_nop 0
	v_addc_co_u32_e32 v17, vcc, 0, v87, vcc
	global_load_dwordx4 v[76:79], v[16:17], off offset:-4096
	v_add_co_u32_e32 v18, vcc, s0, v86
	s_mov_b32 s0, 0x123000
	s_nop 0
	v_addc_co_u32_e32 v19, vcc, 0, v87, vcc
	global_load_dwordx4 v[80:83], v[18:19], off offset:-4096
	global_load_dwordx4 v[88:91], v[16:17], off
	v_add_co_u32_e32 v16, vcc, s0, v86
	s_mov_b32 s0, 0x133000
	s_nop 0
	v_addc_co_u32_e32 v17, vcc, 0, v87, vcc
	global_load_dwordx4 v[68:71], v[16:17], off
	global_load_dwordx4 v[92:95], v[18:19], off
	v_add_co_u32_e32 v16, vcc, s0, v86
	s_mov_b64 s[0:1], 0x40000
	s_nop 0
	v_addc_co_u32_e32 v17, vcc, 0, v87, vcc
	global_load_dwordx4 v[96:99], v[16:17], off offset:-4096
	s_nop 0
	global_load_dwordx4 v[16:19], v[16:17], off
	s_waitcnt vmcnt(0)
	v_lshlrev_b32_e32 v86, 16, v74
	v_and_b32_e32 v87, 0xffff0000, v74
	v_lshlrev_b32_e32 v74, 16, v75
	v_and_b32_e32 v75, 0xffff0000, v75
	v_pk_mul_f32 v[66:67], v[66:67], v[74:75]
	v_lshlrev_b32_e32 v74, 16, v72
	v_and_b32_e32 v75, 0xffff0000, v72
	v_lshlrev_b32_e32 v72, 16, v73
	v_and_b32_e32 v73, 0xffff0000, v73
	v_pk_mul_f32 v[64:65], v[64:65], v[86:87]
	v_pk_mul_f32 v[62:63], v[62:63], v[72:73]
	v_pk_mul_f32 v[60:61], v[60:61], v[74:75]
	s_nop 0
	v_cvt_pk_bf16_f32 v60, v60, v61
	v_cvt_pk_bf16_f32 v61, v62, v63
	v_cvt_pk_bf16_f32 v62, v64, v65
	v_lshl_add_u64 v[64:65], v[84:85], 0, s[0:1]
	s_mov_b32 s0, 0x40000
	v_cvt_pk_bf16_f32 v63, v66, v67
	v_add_co_u32_e32 v66, vcc, s0, v84
	s_mov_b64 s[0:1], 0x48000
	s_nop 0
	v_addc_co_u32_e32 v67, vcc, 0, v85, vcc
	global_store_dwordx4 v[66:67], v[60:63], off
	s_nop 1
	v_lshlrev_b32_e32 v60, 16, v78
	v_and_b32_e32 v61, 0xffff0000, v78
	v_lshlrev_b32_e32 v62, 16, v79
	v_and_b32_e32 v63, 0xffff0000, v79
	v_pk_mul_f32 v[58:59], v[58:59], v[62:63]
	v_pk_mul_f32 v[56:57], v[56:57], v[60:61]
	v_lshlrev_b32_e32 v60, 16, v76
	v_and_b32_e32 v61, 0xffff0000, v76
	v_lshlrev_b32_e32 v62, 16, v77
	v_and_b32_e32 v63, 0xffff0000, v77
	v_pk_mul_f32 v[54:55], v[54:55], v[62:63]
	v_pk_mul_f32 v[52:53], v[52:53], v[60:61]
	s_nop 0
	v_cvt_pk_bf16_f32 v52, v52, v53
	v_cvt_pk_bf16_f32 v53, v54, v55
	v_cvt_pk_bf16_f32 v54, v56, v57
	v_cvt_pk_bf16_f32 v55, v58, v59
	global_store_dwordx4 v[64:65], v[52:55], off offset:256
	s_nop 1
	v_lshlrev_b32_e32 v52, 16, v82
	v_and_b32_e32 v53, 0xffff0000, v82
	v_lshlrev_b32_e32 v54, 16, v83
	v_and_b32_e32 v55, 0xffff0000, v83
	v_pk_mul_f32 v[50:51], v[50:51], v[54:55]
	v_pk_mul_f32 v[48:49], v[48:49], v[52:53]
	v_lshlrev_b32_e32 v52, 16, v80
	v_and_b32_e32 v53, 0xffff0000, v80
	v_lshlrev_b32_e32 v54, 16, v81
	v_and_b32_e32 v55, 0xffff0000, v81
	v_pk_mul_f32 v[46:47], v[46:47], v[54:55]
	v_pk_mul_f32 v[44:45], v[44:45], v[52:53]
	s_nop 0
	v_cvt_pk_bf16_f32 v44, v44, v45
	v_cvt_pk_bf16_f32 v45, v46, v47
	v_cvt_pk_bf16_f32 v46, v48, v49
	v_lshl_add_u64 v[48:49], v[84:85], 0, s[0:1]
	s_mov_b32 s0, 0x48000
	v_cvt_pk_bf16_f32 v47, v50, v51
	v_add_co_u32_e32 v50, vcc, s0, v84
	s_mov_b64 s[0:1], 0x50000
	s_nop 0
	v_addc_co_u32_e32 v51, vcc, 0, v85, vcc
	global_store_dwordx4 v[50:51], v[44:47], off
	s_nop 1
	v_lshlrev_b32_e32 v44, 16, v90
	v_and_b32_e32 v45, 0xffff0000, v90
	v_lshlrev_b32_e32 v46, 16, v91
	v_and_b32_e32 v47, 0xffff0000, v91
	v_pk_mul_f32 v[42:43], v[42:43], v[46:47]
	v_pk_mul_f32 v[40:41], v[40:41], v[44:45]
	v_lshlrev_b32_e32 v44, 16, v88
	v_and_b32_e32 v45, 0xffff0000, v88
	v_lshlrev_b32_e32 v46, 16, v89
	v_and_b32_e32 v47, 0xffff0000, v89
	v_pk_mul_f32 v[38:39], v[38:39], v[46:47]
	v_pk_mul_f32 v[36:37], v[36:37], v[44:45]
	s_nop 0
	v_cvt_pk_bf16_f32 v36, v36, v37
	v_cvt_pk_bf16_f32 v37, v38, v39
	v_cvt_pk_bf16_f32 v38, v40, v41
	v_cvt_pk_bf16_f32 v39, v42, v43
	global_store_dwordx4 v[48:49], v[36:39], off offset:256
	s_nop 1
	v_lshlrev_b32_e32 v36, 16, v94
	v_and_b32_e32 v37, 0xffff0000, v94
	v_lshlrev_b32_e32 v38, 16, v95
	v_and_b32_e32 v39, 0xffff0000, v95
	v_pk_mul_f32 v[34:35], v[34:35], v[38:39]
	v_pk_mul_f32 v[32:33], v[32:33], v[36:37]
	v_lshlrev_b32_e32 v36, 16, v92
	v_and_b32_e32 v37, 0xffff0000, v92
	v_lshlrev_b32_e32 v38, 16, v93
	v_and_b32_e32 v39, 0xffff0000, v93
	v_pk_mul_f32 v[30:31], v[30:31], v[38:39]
	v_pk_mul_f32 v[28:29], v[28:29], v[36:37]
	s_nop 0
	v_cvt_pk_bf16_f32 v28, v28, v29
	v_cvt_pk_bf16_f32 v29, v30, v31
	v_cvt_pk_bf16_f32 v30, v32, v33
	v_lshl_add_u64 v[32:33], v[84:85], 0, s[0:1]
	s_mov_b32 s0, 0x50000
	v_cvt_pk_bf16_f32 v31, v34, v35
	v_add_co_u32_e32 v34, vcc, s0, v84
	s_mov_b64 s[0:1], 0x58000
	s_nop 0
	v_addc_co_u32_e32 v35, vcc, 0, v85, vcc
	global_store_dwordx4 v[34:35], v[28:31], off
	s_nop 1
	v_lshlrev_b32_e32 v28, 16, v98
	v_and_b32_e32 v29, 0xffff0000, v98
	v_lshlrev_b32_e32 v30, 16, v99
	v_and_b32_e32 v31, 0xffff0000, v99
	v_pk_mul_f32 v[26:27], v[26:27], v[30:31]
	v_pk_mul_f32 v[24:25], v[24:25], v[28:29]
	v_lshlrev_b32_e32 v28, 16, v96
	v_and_b32_e32 v29, 0xffff0000, v96
	v_lshlrev_b32_e32 v30, 16, v97
	v_and_b32_e32 v31, 0xffff0000, v97
	v_pk_mul_f32 v[22:23], v[22:23], v[30:31]
	v_pk_mul_f32 v[20:21], v[20:21], v[28:29]
	s_nop 0
	v_cvt_pk_bf16_f32 v20, v20, v21
	v_cvt_pk_bf16_f32 v21, v22, v23
	v_cvt_pk_bf16_f32 v22, v24, v25
	v_cvt_pk_bf16_f32 v23, v26, v27
	global_store_dwordx4 v[32:33], v[20:23], off offset:256
	s_nop 1
	v_lshlrev_b32_e32 v20, 16, v70
	v_and_b32_e32 v21, 0xffff0000, v70
	v_lshlrev_b32_e32 v22, 16, v71
	v_and_b32_e32 v23, 0xffff0000, v71
	v_pk_mul_f32 v[22:23], v[10:11], v[22:23]
	v_pk_mul_f32 v[10:11], v[8:9], v[20:21]
	v_lshlrev_b32_e32 v8, 16, v68
	v_and_b32_e32 v9, 0xffff0000, v68
	v_lshlrev_b32_e32 v20, 16, v69
	v_and_b32_e32 v21, 0xffff0000, v69
	v_pk_mul_f32 v[14:15], v[14:15], v[20:21]
	v_pk_mul_f32 v[8:9], v[12:13], v[8:9]
	v_lshl_add_u64 v[12:13], v[84:85], 0, s[0:1]
	s_mov_b32 s0, 0x58000
	v_cvt_pk_bf16_f32 v8, v8, v9
	v_cvt_pk_bf16_f32 v9, v14, v15
	v_add_co_u32_e32 v14, vcc, s0, v84
	v_cvt_pk_bf16_f32 v10, v10, v11
	v_cvt_pk_bf16_f32 v11, v22, v23
	s_nop 1
	v_addc_co_u32_e32 v15, vcc, 0, v85, vcc
	global_store_dwordx4 v[14:15], v[8:11], off
	s_nop 1
	v_lshlrev_b32_e32 v8, 16, v18
	v_and_b32_e32 v9, 0xffff0000, v18
	v_lshlrev_b32_e32 v10, 16, v19
	v_and_b32_e32 v11, 0xffff0000, v19
	v_pk_mul_f32 v[10:11], v[2:3], v[10:11]
	v_pk_mul_f32 v[2:3], v[0:1], v[8:9]
	v_lshlrev_b32_e32 v0, 16, v16
	v_and_b32_e32 v1, 0xffff0000, v16
	v_lshlrev_b32_e32 v8, 16, v17
	v_and_b32_e32 v9, 0xffff0000, v17
	v_pk_mul_f32 v[0:1], v[4:5], v[0:1]
	v_pk_mul_f32 v[6:7], v[6:7], v[8:9]
	v_cvt_pk_bf16_f32 v0, v0, v1
	v_cvt_pk_bf16_f32 v2, v2, v3
	v_cvt_pk_bf16_f32 v3, v10, v11
	s_nop 0
	v_cvt_pk_bf16_f32 v1, v6, v7
	global_store_dwordx4 v[12:13], v[0:3], off offset:256
	s_waitcnt vmcnt(0)
	s_cbranch_scc1 .LBB0_821
